# P5 mix GEMM epilogue: residual x rows (read once) loaded with the non-temporal hint
# baseline (speedup 1.0000x reference)
; __device__ __forceinline__ unsigned cvt_pk_bf16(float lo, float hi) { unsigned r; asm volatile("v_cvt_pk_bf16_f32 %0, %1, %2" : "=v"(r) : "v"(lo), "v"(hi)); return r; }
;     __device__ __forceinline__ void operator()(const f32x4 (&acc)[2][2][4][2], const Unit& u, int wr, int wc, int fr, int fq) const {
;         const int row0 = u.pm * BM + wr * 64 + fr, col0 = u.pn * BM + wc * 32 + 8 * fq;
; #pragma unroll
;         for (int ai = 0; ai < 2; ++ai)
; #pragma unroll
;             for (int m = 0; m < 4; ++m) {
;                 const int row = row0 + ai * HALF + m * 16;
;                 const float* xr = (row < 16384 ? xp + (size_t)row * 4096 : xs + (size_t)(row - 16384) * 4096) + col0;
;                 bf16_t* orow = O + (size_t)row * 4096 + col0;
; #pragma unroll
;                 for (int bj = 0; bj < 2; ++bj) { if (!((u.mask >> (2 * ai + bj)) & 1)) continue;
;                     const f32x4 x0 = *(const f32x4*)(xr + bj * HALF), x1 = *(const f32x4*)(xr + bj * HALF + 4);
;                     const f32x4 v0 = acc[ai][bj][m][0] + alpha * x0, v1 = acc[ai][bj][m][1] + alpha * x1;
;                     u32x4 w; w.x = cvt_pk_bf16(v0[0], v0[1]); w.y = cvt_pk_bf16(v0[2], v0[3]); w.z = cvt_pk_bf16(v1[0], v1[1]); w.w = cvt_pk_bf16(v1[2], v1[3]);
;                     *(u32x4*)(orow + bj * HALF) = w; }
.LBB0_1372:
	v_lshl_add_u32 v144, s24, 8, v150
	v_readlane_b32 s56, v253, 0
	v_readlane_b32 s57, v253, 1
	v_readlane_b32 s58, v253, 2
	v_readlane_b32 s59, v253, 3
	v_cmp_lt_i32_e32 vcc, s48, v144
	v_lshl_or_b32 v146, s22, 8, v152
	v_add_u32_e32 v226, 0xffffc000, v144
	v_ashrrev_i32_e32 v147, 31, v146
	v_mov_b32_e32 v148, s56
	v_mov_b32_e32 v149, s57
	v_mov_b32_e32 v224, s58
	v_mov_b32_e32 v225, s59
	v_cndmask_b32_e32 v226, v144, v226, vcc
	v_cndmask_b32_e32 v148, v148, v224, vcc
	v_cndmask_b32_e32 v149, v149, v225, vcc
	v_mov_b32_e32 v227, 0
	v_mov_b32_e32 v228, v144
	v_mov_b32_e32 v229, 0
	v_lshlrev_b64 v[226:227], 14, v[226:227]
	v_lshlrev_b64 v[228:229], 13, v[228:229]
	v_lshl_add_u64 v[148:149], v[148:149], 0, v[226:227]
	v_lshl_add_u64 v[228:229], s[4:5], 0, v[228:229]
	v_lshl_add_u64 v[148:149], v[146:147], 2, v[148:149]
	v_lshl_add_u64 v[228:229], v[146:147], 1, v[228:229]
	s_mov_b32 s61, 0
	global_load_dwordx4 v[156:159], v[148:149], off nt
	global_load_dwordx4 v[160:163], v[148:149], off offset:16 nt
	global_load_dwordx4 v[164:167], v[148:149], off offset:512 nt
	global_load_dwordx4 v[168:171], v[148:149], off offset:528 nt
	s_mov_b32 s60, 0x40000
	v_lshl_add_u64 v[224:225], v[148:149], 0, s[60:61]
	global_load_dwordx4 v[172:175], v[224:225], off nt
	global_load_dwordx4 v[176:179], v[224:225], off offset:16 nt
	global_load_dwordx4 v[180:183], v[224:225], off offset:512 nt
	global_load_dwordx4 v[184:187], v[224:225], off offset:528 nt
	s_mov_b32 s60, 0x80000
	v_lshl_add_u64 v[224:225], v[148:149], 0, s[60:61]
	global_load_dwordx4 v[188:191], v[224:225], off nt
	global_load_dwordx4 v[192:195], v[224:225], off offset:16 nt
	global_load_dwordx4 v[196:199], v[224:225], off offset:512 nt
	global_load_dwordx4 v[200:203], v[224:225], off offset:528 nt
	s_mov_b32 s60, 0xc0000
	v_lshl_add_u64 v[224:225], v[148:149], 0, s[60:61]
	global_load_dwordx4 v[204:207], v[224:225], off nt
	global_load_dwordx4 v[208:211], v[224:225], off offset:16 nt
	global_load_dwordx4 v[212:215], v[224:225], off offset:512 nt
	global_load_dwordx4 v[216:219], v[224:225], off offset:528 nt
	s_waitcnt vmcnt(12)
	v_pk_fma_f32 v[124:125], v[156:157], s[10:11], v[124:125] op_sel_hi:[1,0,1]
	v_pk_fma_f32 v[126:127], v[158:159], s[10:11], v[126:127] op_sel_hi:[1,0,1]
	v_pk_fma_f32 v[120:121], v[160:161], s[10:11], v[120:121] op_sel_hi:[1,0,1]
	v_pk_fma_f32 v[122:123], v[162:163], s[10:11], v[122:123] op_sel_hi:[1,0,1]
	v_pk_fma_f32 v[116:117], v[164:165], s[10:11], v[116:117] op_sel_hi:[1,0,1]
	v_pk_fma_f32 v[118:119], v[166:167], s[10:11], v[118:119] op_sel_hi:[1,0,1]
	v_pk_fma_f32 v[112:113], v[168:169], s[10:11], v[112:113] op_sel_hi:[1,0,1]
	v_pk_fma_f32 v[114:115], v[170:171], s[10:11], v[114:115] op_sel_hi:[1,0,1]
	v_cvt_pk_bf16_f32 v124, v124, v125
	v_cvt_pk_bf16_f32 v125, v126, v127
	v_cvt_pk_bf16_f32 v126, v120, v121
	v_cvt_pk_bf16_f32 v127, v122, v123
	v_cvt_pk_bf16_f32 v116, v116, v117
	v_cvt_pk_bf16_f32 v117, v118, v119
	v_cvt_pk_bf16_f32 v118, v112, v113
	v_cvt_pk_bf16_f32 v119, v114, v115
	s_mov_b32 s60, 0x200000
	v_lshl_add_u64 v[224:225], v[148:149], 0, s[60:61]
	global_load_dwordx4 v[156:159], v[224:225], off nt
	global_load_dwordx4 v[160:163], v[224:225], off offset:16 nt
	global_load_dwordx4 v[164:167], v[224:225], off offset:512 nt
	global_load_dwordx4 v[168:171], v[224:225], off offset:528 nt
	s_waitcnt vmcnt(12)
	v_pk_fma_f32 v[108:109], v[172:173], s[10:11], v[108:109] op_sel_hi:[1,0,1]
	v_pk_fma_f32 v[110:111], v[174:175], s[10:11], v[110:111] op_sel_hi:[1,0,1]
	v_pk_fma_f32 v[104:105], v[176:177], s[10:11], v[104:105] op_sel_hi:[1,0,1]
	v_pk_fma_f32 v[106:107], v[178:179], s[10:11], v[106:107] op_sel_hi:[1,0,1]
	v_pk_fma_f32 v[100:101], v[180:181], s[10:11], v[100:101] op_sel_hi:[1,0,1]
	v_pk_fma_f32 v[102:103], v[182:183], s[10:11], v[102:103] op_sel_hi:[1,0,1]
	v_pk_fma_f32 v[96:97], v[184:185], s[10:11], v[96:97] op_sel_hi:[1,0,1]
	v_pk_fma_f32 v[98:99], v[186:187], s[10:11], v[98:99] op_sel_hi:[1,0,1]
	v_cvt_pk_bf16_f32 v108, v108, v109
	v_cvt_pk_bf16_f32 v109, v110, v111
	v_cvt_pk_bf16_f32 v110, v104, v105
	v_cvt_pk_bf16_f32 v111, v106, v107
	v_cvt_pk_bf16_f32 v100, v100, v101
	v_cvt_pk_bf16_f32 v101, v102, v103
	v_cvt_pk_bf16_f32 v102, v96, v97
	v_cvt_pk_bf16_f32 v103, v98, v99
	s_mov_b32 s60, 0x240000
	v_lshl_add_u64 v[224:225], v[148:149], 0, s[60:61]
	global_load_dwordx4 v[172:175], v[224:225], off nt
	global_load_dwordx4 v[176:179], v[224:225], off offset:16 nt
	global_load_dwordx4 v[180:183], v[224:225], off offset:512 nt
	global_load_dwordx4 v[184:187], v[224:225], off offset:528 nt
	s_waitcnt vmcnt(12)
	v_pk_fma_f32 v[92:93], v[188:189], s[10:11], v[92:93] op_sel_hi:[1,0,1]
	v_pk_fma_f32 v[94:95], v[190:191], s[10:11], v[94:95] op_sel_hi:[1,0,1]
	v_pk_fma_f32 v[88:89], v[192:193], s[10:11], v[88:89] op_sel_hi:[1,0,1]
	v_pk_fma_f32 v[90:91], v[194:195], s[10:11], v[90:91] op_sel_hi:[1,0,1]
	v_pk_fma_f32 v[84:85], v[196:197], s[10:11], v[84:85] op_sel_hi:[1,0,1]
	v_pk_fma_f32 v[86:87], v[198:199], s[10:11], v[86:87] op_sel_hi:[1,0,1]
	v_pk_fma_f32 v[80:81], v[200:201], s[10:11], v[80:81] op_sel_hi:[1,0,1]
	v_pk_fma_f32 v[82:83], v[202:203], s[10:11], v[82:83] op_sel_hi:[1,0,1]
	v_cvt_pk_bf16_f32 v92, v92, v93
	v_cvt_pk_bf16_f32 v93, v94, v95
	v_cvt_pk_bf16_f32 v94, v88, v89
	v_cvt_pk_bf16_f32 v95, v90, v91
	v_cvt_pk_bf16_f32 v84, v84, v85
	v_cvt_pk_bf16_f32 v85, v86, v87
	v_cvt_pk_bf16_f32 v86, v80, v81
	v_cvt_pk_bf16_f32 v87, v82, v83
	s_mov_b32 s60, 0x280000
	v_lshl_add_u64 v[224:225], v[148:149], 0, s[60:61]
	global_load_dwordx4 v[188:191], v[224:225], off nt
	global_load_dwordx4 v[192:195], v[224:225], off offset:16 nt
	global_load_dwordx4 v[196:199], v[224:225], off offset:512 nt
	global_load_dwordx4 v[200:203], v[224:225], off offset:528 nt
	s_waitcnt vmcnt(12)
; __device__ __forceinline__ unsigned cvt_pk_bf16(float lo, float hi) { unsigned r; asm volatile("v_cvt_pk_bf16_f32 %0, %1, %2" : "=v"(r) : "v"(lo), "v"(hi)); return r; }
; #define PG8_BAR __builtin_amdgcn_s_barrier()
;     __device__ __forceinline__ void operator()(const f32x4 (&acc)[2][2][4][2], const Unit& u, int wr, int wc, int fr, int fq) const {
;         const int row0 = u.pm * BM + wr * 64 + fr, col0 = u.pn * BM + wc * 32 + 8 * fq;
; #pragma unroll
;         for (int ai = 0; ai < 2; ++ai)
; #pragma unroll
;             for (int m = 0; m < 4; ++m) {
;                 const int row = row0 + ai * HALF + m * 16;
;                 const float* xr = (row < 16384 ? xp + (size_t)row * 4096 : xs + (size_t)(row - 16384) * 4096) + col0;
;                 bf16_t* orow = O + (size_t)row * 4096 + col0;
; #pragma unroll
;                 for (int bj = 0; bj < 2; ++bj) { if (!((u.mask >> (2 * ai + bj)) & 1)) continue;
;                     const f32x4 x0 = *(const f32x4*)(xr + bj * HALF), x1 = *(const f32x4*)(xr + bj * HALF + 4);
;                     const f32x4 v0 = acc[ai][bj][m][0] + alpha * x0, v1 = acc[ai][bj][m][1] + alpha * x1;
;                     u32x4 w; w.x = cvt_pk_bf16(v0[0], v0[1]); w.y = cvt_pk_bf16(v0[2], v0[3]); w.z = cvt_pk_bf16(v1[0], v1[1]); w.w = cvt_pk_bf16(v1[2], v1[3]);
;                     *(u32x4*)(orow + bj * HALF) = w; }
; template <class Epi, class Sched, bool ALIGN_EPI = false, bool SP2 = false>
; __device__ __forceinline__ void gemm_phase(PG8_LAS unsigned char* lds, const Gemm g, const Sched& S, const Epi& E, int tid_in) {
;     ...
;         cur = nxt; cA = nA; cB = nB; ++ui;
;         if constexpr (ALIGN_EPI) { if (wr == 1) PG8_BAR; }
	v_pk_fma_f32 v[76:77], v[204:205], s[10:11], v[76:77] op_sel_hi:[1,0,1]
	v_pk_fma_f32 v[78:79], v[206:207], s[10:11], v[78:79] op_sel_hi:[1,0,1]
	v_pk_fma_f32 v[72:73], v[208:209], s[10:11], v[72:73] op_sel_hi:[1,0,1]
	v_pk_fma_f32 v[74:75], v[210:211], s[10:11], v[74:75] op_sel_hi:[1,0,1]
	v_pk_fma_f32 v[68:69], v[212:213], s[10:11], v[68:69] op_sel_hi:[1,0,1]
	v_pk_fma_f32 v[70:71], v[214:215], s[10:11], v[70:71] op_sel_hi:[1,0,1]
	v_pk_fma_f32 v[64:65], v[216:217], s[10:11], v[64:65] op_sel_hi:[1,0,1]
	v_pk_fma_f32 v[66:67], v[218:219], s[10:11], v[66:67] op_sel_hi:[1,0,1]
	v_cvt_pk_bf16_f32 v76, v76, v77
	v_cvt_pk_bf16_f32 v77, v78, v79
	v_cvt_pk_bf16_f32 v78, v72, v73
	v_cvt_pk_bf16_f32 v79, v74, v75
	v_cvt_pk_bf16_f32 v68, v68, v69
	v_cvt_pk_bf16_f32 v69, v70, v71
	v_cvt_pk_bf16_f32 v70, v64, v65
	v_cvt_pk_bf16_f32 v71, v66, v67
	s_mov_b32 s60, 0x2c0000
	v_lshl_add_u64 v[224:225], v[148:149], 0, s[60:61]
	global_load_dwordx4 v[204:207], v[224:225], off nt
	global_load_dwordx4 v[208:211], v[224:225], off offset:16 nt
	global_load_dwordx4 v[212:215], v[224:225], off offset:512 nt
	global_load_dwordx4 v[216:219], v[224:225], off offset:528 nt
	s_waitcnt vmcnt(12)
	v_pk_fma_f32 v[60:61], v[156:157], s[10:11], v[60:61] op_sel_hi:[1,0,1]
	v_pk_fma_f32 v[62:63], v[158:159], s[10:11], v[62:63] op_sel_hi:[1,0,1]
	v_pk_fma_f32 v[56:57], v[160:161], s[10:11], v[56:57] op_sel_hi:[1,0,1]
	v_pk_fma_f32 v[58:59], v[162:163], s[10:11], v[58:59] op_sel_hi:[1,0,1]
	v_pk_fma_f32 v[52:53], v[164:165], s[10:11], v[52:53] op_sel_hi:[1,0,1]
	v_pk_fma_f32 v[54:55], v[166:167], s[10:11], v[54:55] op_sel_hi:[1,0,1]
	v_pk_fma_f32 v[48:49], v[168:169], s[10:11], v[48:49] op_sel_hi:[1,0,1]
	v_pk_fma_f32 v[50:51], v[170:171], s[10:11], v[50:51] op_sel_hi:[1,0,1]
	v_cvt_pk_bf16_f32 v60, v60, v61
	v_cvt_pk_bf16_f32 v61, v62, v63
	v_cvt_pk_bf16_f32 v62, v56, v57
	v_cvt_pk_bf16_f32 v63, v58, v59
	v_cvt_pk_bf16_f32 v52, v52, v53
	v_cvt_pk_bf16_f32 v53, v54, v55
	v_cvt_pk_bf16_f32 v54, v48, v49
	v_cvt_pk_bf16_f32 v55, v50, v51
	s_waitcnt vmcnt(8)
	v_pk_fma_f32 v[44:45], v[172:173], s[10:11], v[44:45] op_sel_hi:[1,0,1]
	v_pk_fma_f32 v[46:47], v[174:175], s[10:11], v[46:47] op_sel_hi:[1,0,1]
	v_pk_fma_f32 v[40:41], v[176:177], s[10:11], v[40:41] op_sel_hi:[1,0,1]
	v_pk_fma_f32 v[42:43], v[178:179], s[10:11], v[42:43] op_sel_hi:[1,0,1]
	v_pk_fma_f32 v[36:37], v[180:181], s[10:11], v[36:37] op_sel_hi:[1,0,1]
	v_pk_fma_f32 v[38:39], v[182:183], s[10:11], v[38:39] op_sel_hi:[1,0,1]
	v_pk_fma_f32 v[32:33], v[184:185], s[10:11], v[32:33] op_sel_hi:[1,0,1]
	v_pk_fma_f32 v[34:35], v[186:187], s[10:11], v[34:35] op_sel_hi:[1,0,1]
	v_cvt_pk_bf16_f32 v44, v44, v45
	v_cvt_pk_bf16_f32 v45, v46, v47
	v_cvt_pk_bf16_f32 v46, v40, v41
	v_cvt_pk_bf16_f32 v47, v42, v43
	v_cvt_pk_bf16_f32 v36, v36, v37
	v_cvt_pk_bf16_f32 v37, v38, v39
	v_cvt_pk_bf16_f32 v38, v32, v33
	v_cvt_pk_bf16_f32 v39, v34, v35
	s_waitcnt vmcnt(4)
	v_pk_fma_f32 v[28:29], v[188:189], s[10:11], v[28:29] op_sel_hi:[1,0,1]
	v_pk_fma_f32 v[30:31], v[190:191], s[10:11], v[30:31] op_sel_hi:[1,0,1]
	v_pk_fma_f32 v[24:25], v[192:193], s[10:11], v[24:25] op_sel_hi:[1,0,1]
	v_pk_fma_f32 v[26:27], v[194:195], s[10:11], v[26:27] op_sel_hi:[1,0,1]
	v_pk_fma_f32 v[20:21], v[196:197], s[10:11], v[20:21] op_sel_hi:[1,0,1]
	v_pk_fma_f32 v[22:23], v[198:199], s[10:11], v[22:23] op_sel_hi:[1,0,1]
	v_pk_fma_f32 v[16:17], v[200:201], s[10:11], v[16:17] op_sel_hi:[1,0,1]
	v_pk_fma_f32 v[18:19], v[202:203], s[10:11], v[18:19] op_sel_hi:[1,0,1]
	v_cvt_pk_bf16_f32 v28, v28, v29
	v_cvt_pk_bf16_f32 v29, v30, v31
	v_cvt_pk_bf16_f32 v30, v24, v25
	v_cvt_pk_bf16_f32 v31, v26, v27
	v_cvt_pk_bf16_f32 v20, v20, v21
	v_cvt_pk_bf16_f32 v21, v22, v23
	v_cvt_pk_bf16_f32 v22, v16, v17
	v_cvt_pk_bf16_f32 v23, v18, v19
	s_waitcnt vmcnt(0)
	v_pk_fma_f32 v[12:13], v[204:205], s[10:11], v[12:13] op_sel_hi:[1,0,1]
	v_pk_fma_f32 v[14:15], v[206:207], s[10:11], v[14:15] op_sel_hi:[1,0,1]
	v_pk_fma_f32 v[8:9], v[208:209], s[10:11], v[8:9] op_sel_hi:[1,0,1]
	v_pk_fma_f32 v[10:11], v[210:211], s[10:11], v[10:11] op_sel_hi:[1,0,1]
	v_pk_fma_f32 v[4:5], v[212:213], s[10:11], v[4:5] op_sel_hi:[1,0,1]
	v_pk_fma_f32 v[6:7], v[214:215], s[10:11], v[6:7] op_sel_hi:[1,0,1]
	v_pk_fma_f32 v[0:1], v[216:217], s[10:11], v[0:1] op_sel_hi:[1,0,1]
	v_pk_fma_f32 v[2:3], v[218:219], s[10:11], v[2:3] op_sel_hi:[1,0,1]
	v_cvt_pk_bf16_f32 v12, v12, v13
	v_cvt_pk_bf16_f32 v13, v14, v15
	v_cvt_pk_bf16_f32 v14, v8, v9
	v_cvt_pk_bf16_f32 v15, v10, v11
	v_cvt_pk_bf16_f32 v4, v4, v5
	v_cvt_pk_bf16_f32 v5, v6, v7
	v_cvt_pk_bf16_f32 v6, v0, v1
	v_cvt_pk_bf16_f32 v7, v2, v3
	global_store_dwordx4 v[228:229], v[124:127], off
	global_store_dwordx4 v[228:229], v[116:119], off offset:256
	s_mov_b32 s60, 0x20000
	v_lshl_add_u64 v[224:225], v[228:229], 0, s[60:61]
	global_store_dwordx4 v[224:225], v[108:111], off
	global_store_dwordx4 v[224:225], v[100:103], off offset:256
	s_mov_b32 s60, 0x40000
	v_lshl_add_u64 v[224:225], v[228:229], 0, s[60:61]
	global_store_dwordx4 v[224:225], v[92:95], off
	global_store_dwordx4 v[224:225], v[84:87], off offset:256
	s_mov_b32 s60, 0x60000
	v_lshl_add_u64 v[224:225], v[228:229], 0, s[60:61]
	global_store_dwordx4 v[224:225], v[76:79], off
	global_store_dwordx4 v[224:225], v[68:71], off offset:256
	s_mov_b32 s60, 0x100000
	v_lshl_add_u64 v[224:225], v[228:229], 0, s[60:61]
	global_store_dwordx4 v[224:225], v[60:63], off
	global_store_dwordx4 v[224:225], v[52:55], off offset:256
	s_mov_b32 s60, 0x120000
	v_lshl_add_u64 v[224:225], v[228:229], 0, s[60:61]
	global_store_dwordx4 v[224:225], v[44:47], off
	global_store_dwordx4 v[224:225], v[36:39], off offset:256
	s_mov_b32 s60, 0x140000
	v_lshl_add_u64 v[224:225], v[228:229], 0, s[60:61]
	global_store_dwordx4 v[224:225], v[28:31], off
	global_store_dwordx4 v[224:225], v[20:23], off offset:256
	s_mov_b32 s60, 0x160000
	v_lshl_add_u64 v[224:225], v[228:229], 0, s[60:61]
	global_store_dwordx4 v[224:225], v[12:15], off
	global_store_dwordx4 v[224:225], v[4:7], off offset:256
	s_andn2_b64 vcc, exec, s[18:19]
	s_mov_b64 s[18:19], -1
	s_nop 1
	s_cbranch_vccnz .LBB0_1364
	s_andn2_b64 vcc, exec, s[0:1]
	s_cbranch_vccnz .LBB0_1363
	s_barrier
	s_branch .LBB0_1363
